# attn0 and attn2 unit prologues: tile0+tile1(+tile2) loads issued together with counted vmcnt waits (on top of attn1 prologue change)
# baseline (speedup 1.0000x reference)
;     ...
;         auto gload = [&](u32x4 (&rg)[NJ], float& ckr, int t) {
; #pragma unroll
;             for (int j = 0; j < NJ; ++j) rg[j] = *(const u32x4*)(src[j] + (size_t)t * step[j]);
;             if (MODE == 1 && tid < 64) ckr = ckp[t * 64 + tid];
;         };
;         auto lstore = [&](const u32x4 (&rg)[NJ], const float ckr, int stg) {
;             unsigned char* sb = lds + stg * STG;
; #pragma unroll
;             for (int j = 0; j < NJ; ++j) {
;                 if (j < NKJ) *(u32x4*)(sb + j * 9216 + lrow * 144 + lkc * 16) = rg[j];
;                 else { unsigned char* d = sb + VT_OFF + (lrow + 64 * (j - NKJ)) * 136 + lkc * 16; u32x2 a, c; a.x = rg[j].x; a.y = rg[j].y; c.x = rg[j].z; c.y = rg[j].w; *(u32x2*)d = a; *(u32x2*)(d + 8) = c; }
;     ...
;         gload(rgE, ckrE, j0); lstore(rgE, ckrE, 0);
;         if (ntl > 1) { gload(rgE, ckrE, j0 + 1); lstore(rgE, ckrE, 1); }
;         if (DEEP && ntl > 2) gload(rgO, ckrO, j0 + 2);
;         if (MODE == 2 && ntl > 1) wnext = mrow[j0 + 1];
;         __syncthreads();
.LBB0_1255:
	s_ashr_i32 s0, s95, 31
	s_lshr_b32 s0, s0, 30
	s_add_i32 s0, s95, s0
	s_ashr_i32 s8, s0, 2
	s_and_b32 s0, s0, 0x1fffffc
	s_lshl_b32 s11, s8, 13
	s_sub_i32 s9, s95, s0
	s_lshl_b32 s10, s94, 7
	v_or_b32_e32 v10, s11, v191
	v_mov_b64_e32 v[12:13], s[74:75]
	v_or_b32_e32 v186, s10, v219
	v_mad_i64_i32 v[4:5], s[0:1], v10, s88, v[12:13]
	s_lshl_b32 s84, s9, 7
	v_or_b32_e32 v201, v186, v185
	s_ashr_i32 s85, s84, 31
	s_lshl_b32 s0, s8, 9
	v_lshl_add_u64 v[4:5], s[84:85], 1, v[4:5]
	v_lshlrev_b32_e32 v2, 1, v184
	s_add_i32 s0, s0, s84
	v_add_u32_e32 v14, s84, v220
	v_add_u32_e32 v200, s11, v201
	v_lshl_add_u64 v[8:9], v[4:5], 0, v[2:3]
	v_or_b32_e32 v4, s0, v191
	v_mad_i64_i32 v[12:13], s[0:1], v200, s88, v[12:13]
	v_ashrrev_i32_e32 v15, 31, v14
	v_ashrrev_i32_e32 v5, 31, v4
	v_lshl_add_u64 v[12:13], v[14:15], 1, v[12:13]
	v_mov_b32_e32 v197, v3
	v_lshlrev_b64 v[6:7], 14, v[4:5]
	v_lshl_add_u64 v[12:13], v[12:13], 0, v[196:197]
	v_lshl_add_u64 v[4:5], v[188:189], 0, v[6:7]
	global_load_dwordx4 v[150:153], v[12:13], off
	global_load_dwordx4 v[170:173], v[8:9], off offset:1152
	global_load_dwordx4 v[166:169], v[8:9], off offset:1024
	global_load_dwordx4 v[174:177], v[4:5], off
	v_add_co_u32_e32 v14, vcc, s89, v4
	s_addk_i32 s10, 0x80
	s_nop 0
	v_addc_co_u32_e32 v15, vcc, 0, v5, vcc
	global_load_dwordx4 v[154:157], v[12:13], off offset:96
	global_load_dwordx4 v[178:181], v[14:15], off
	global_load_dwordx4 v[158:161], v[12:13], off offset:32
	global_load_dwordx4 v[162:165], v[12:13], off offset:64
	v_add_u32_e32 v2, 0x4800, v245
	s_ashr_i32 s96, s10, 6
	s_cmp_lt_i32 s96, 2
	s_cbranch_scc1 .Lpd0_slow
	v_lshl_add_u64 v[8:9], v[8:9], 0, s[78:79]
	v_add_co_u32_e32 v8, vcc, 0x60000, v8
	s_nop 1
	v_addc_co_u32_e32 v9, vcc, 0, v9, vcc
	global_load_dwordx4 v[114:117], v[8:9], off offset:128
	global_load_dwordx4 v[118:121], v[8:9], off
	global_load_dwordx4 v[122:125], v[4:5], off offset:128
	v_add_co_u32_e32 v4, vcc, 0x100000, v4
	s_nop 1
	v_addc_co_u32_e32 v5, vcc, 0, v5, vcc
	global_load_dwordx4 v[126:129], v[4:5], off offset:128
	s_waitcnt vmcnt(9)
	ds_write_b128 v215, v[166:169]
	ds_write_b128 v215, v[170:173] offset:9216
	s_waitcnt vmcnt(8)
	ds_write2_b64 v2, v[174:175], v[176:177] offset1:1
	v_add_u32_e32 v2, 0x6a00, v245
	s_waitcnt vmcnt(6)
	ds_write2_b64 v2, v[178:179], v[180:181] offset1:1
	v_add_u32_e32 v2, 0xd400, v245
	s_waitcnt vmcnt(2)
	ds_write_b128 v215, v[118:121] offset:35840
	ds_write_b128 v215, v[114:117] offset:45056
	s_waitcnt vmcnt(1)
	ds_write2_b64 v2, v[122:123], v[124:125] offset1:1
	v_add_u32_e32 v2, 0xf600, v245
	s_waitcnt vmcnt(0)
	ds_write2_b64 v2, v[126:127], v[128:129] offset1:1
	s_branch .LBB0_1257
.Lpd0_slow:
	s_cmp_lt_i32 s96, 2
	s_waitcnt vmcnt(5)
	ds_write_b128 v215, v[166:169]
	ds_write_b128 v215, v[170:173] offset:9216
	s_waitcnt vmcnt(4)
	ds_write2_b64 v2, v[174:175], v[176:177] offset1:1
	v_add_u32_e32 v2, 0x6a00, v245
	s_waitcnt vmcnt(2)
	ds_write2_b64 v2, v[178:179], v[180:181] offset1:1
	s_cbranch_scc1 .LBB0_1257
	v_lshl_add_u64 v[8:9], v[8:9], 0, s[78:79]
	v_add_co_u32_e32 v8, vcc, 0x60000, v8
	v_add_u32_e32 v2, 0xd400, v245
	s_nop 0
	v_addc_co_u32_e32 v9, vcc, 0, v9, vcc
	global_load_dwordx4 v[170:173], v[8:9], off offset:128
	global_load_dwordx4 v[166:169], v[8:9], off
	global_load_dwordx4 v[174:177], v[4:5], off offset:128
	v_add_co_u32_e32 v4, vcc, 0x100000, v4
	s_nop 1
	v_addc_co_u32_e32 v5, vcc, 0, v5, vcc
	global_load_dwordx4 v[178:181], v[4:5], off offset:128
	s_waitcnt vmcnt(2)
	ds_write_b128 v215, v[166:169] offset:35840
	ds_write_b128 v215, v[170:173] offset:45056
	s_waitcnt vmcnt(1)
	ds_write2_b64 v2, v[174:175], v[176:177] offset1:1
	v_add_u32_e32 v2, 0xf600, v245
	s_waitcnt vmcnt(0)
	ds_write2_b64 v2, v[178:179], v[180:181] offset1:1

;     ...
;         auto gload = [&](u32x4 (&rg)[NJ], float& ckr, int t) {
; #pragma unroll
;             for (int j = 0; j < NJ; ++j) rg[j] = *(const u32x4*)(src[j] + (size_t)t * step[j]);
;             if (MODE == 1 && tid < 64) ckr = ckp[t * 64 + tid];
;         };
;         auto lstore = [&](const u32x4 (&rg)[NJ], const float ckr, int stg) {
;             unsigned char* sb = lds + stg * STG;
; #pragma unroll
;             for (int j = 0; j < NJ; ++j) {
;                 if (j < NKJ) *(u32x4*)(sb + j * 9216 + lrow * 144 + lkc * 16) = rg[j];
;                 else { unsigned char* d = sb + VT_OFF + (lrow + 64 * (j - NKJ)) * 136 + lkc * 16; u32x2 a, c; a.x = rg[j].x; a.y = rg[j].y; c.x = rg[j].z; c.y = rg[j].w; *(u32x2*)d = a; *(u32x2*)(d + 8) = c; }
;             }
;             if (MODE == 1 && tid < 64) *(float*)(sb + CK_OFF + tid * 4) = ckr;
;     ...
;         gload(rgE, ckrE, j0); lstore(rgE, ckrE, 0);
;         if (ntl > 1) { gload(rgE, ckrE, j0 + 1); lstore(rgE, ckrE, 1); }
;         if (DEEP && ntl > 2) gload(rgO, ckrO, j0 + 2);
;         if (MODE == 2 && ntl > 1) wnext = mrow[j0 + 1];
.LBB0_3597:
	s_ashr_i32 s0, s39, 31
	s_lshr_b32 s0, s0, 28
	s_add_i32 s0, s39, s0
	s_ashr_i32 s4, s0, 4
	s_and_b32 s0, s0, 0x3fffff0
	s_sub_i32 s5, s39, s0
	s_lshl_b32 s7, s4, 13
	s_lshl_b32 s6, s38, 8
	v_or_b32_e32 v1, s7, v171
	v_mov_b64_e32 v[4:5], s[10:11]
	s_lshl_b32 s22, s5, 6
	v_or_b32_e32 v208, s6, v195
	v_mad_i64_i32 v[6:7], s[0:1], v1, s29, v[4:5]
	s_ashr_i32 s23, s22, 31
	s_lshl_b32 s4, s4, 10
	v_or_b32_e32 v2, s7, v194
	s_lshl_b64 s[0:1], s[22:23], 1
	s_add_i32 s4, s4, s22
	v_add_u32_e32 v178, v2, v208
	v_lshl_add_u64 v[8:9], v[6:7], 0, s[0:1]
	v_add_u32_e32 v6, s4, v171
	v_mad_i64_i32 v[4:5], s[4:5], v178, s29, v[4:5]
	v_lshl_add_u64 v[4:5], v[4:5], 0, s[0:1]
	v_mov_b32_e32 v173, v3
	v_lshl_add_u64 v[10:11], v[4:5], 0, v[172:173]
	v_ashrrev_i32_e32 v7, 31, v6
	v_ashrrev_i32_e32 v179, 31, v178
	global_load_dwordx4 v[142:145], v[10:11], off
	global_load_dwordx4 v[146:149], v[10:11], off offset:32
	v_mov_b32_e32 v175, v3
	v_lshlrev_b64 v[6:7], 14, v[6:7]
	v_lshl_add_u64 v[12:13], v[8:9], 0, v[174:175]
	v_lshlrev_b64 v[180:181], 10, v[178:179]
	v_lshl_add_u64 v[4:5], s[14:15], 0, v[180:181]
	v_lshl_add_u64 v[8:9], v[168:169], 0, v[6:7]
	global_load_dwordx4 v[158:161], v[12:13], off offset:2048
	global_load_dwordx2 v[116:117], v[4:5], off
	global_load_dwordx4 v[162:165], v[8:9], off
	global_load_dwordx4 v[150:153], v[10:11], off offset:64
	global_load_dwordx4 v[154:157], v[10:11], off offset:96
	s_addk_i32 s6, 0x100
	s_ashr_i32 s40, s6, 6
	s_cmp_gt_i32 s40, 1
	v_add3_u32 v2, v198, v166, s30
	s_cselect_b64 s[4:5], -1, 0
	v_lshl_add_u64 v[10:11], v[12:13], 0, s[16:17]
	s_cmp_lt_i32 s40, 3
	s_cbranch_scc1 .Lpd2_slow
	v_add_co_u32_e32 v12, vcc, 0x70000, v10
	s_nop 1
	v_addc_co_u32_e32 v13, vcc, 0, v11, vcc
	global_load_dwordx4 v[212:215], v[12:13], off
	global_load_dwordx4 v[216:219], v[8:9], off offset:128
	v_add_co_u32_e32 v10, vcc, 0xe0000, v10
	s_nop 1
	v_addc_co_u32_e32 v11, vcc, 0, v11, vcc
	global_load_dwordx4 v[134:137], v[10:11], off
	global_load_dwordx4 v[138:141], v[8:9], off offset:256
	global_load_dwordx2 v[192:193], v[4:5], off offset:8
	s_waitcnt vmcnt(7)
	ds_write_b128 v205, v[158:161]
	ds_write2_b64 v2, v[162:163], v[164:165] offset1:1
	s_waitcnt vmcnt(4)
	ds_write_b128 v205, v[212:215] offset:18432
	s_waitcnt vmcnt(3)
	ds_write2_b64 v206, v[216:217], v[218:219] offset1:1
	s_branch .LBB0_3601
.Lpd2_slow:
	s_cmp_lt_i32 s40, 2
	s_waitcnt vmcnt(0)
	ds_write_b128 v205, v[158:161]
	ds_write2_b64 v2, v[162:163], v[164:165] offset1:1
	s_cbranch_scc0 .LBB0_3641
	s_cmp_lt_i32 s40, 3
	s_cbranch_scc0 .LBB0_3642
